# ff2 walks its row panels in reverse order so the hidden activations ff1 wrote last are read first (Infinity-Cache reuse)
# speedup vs baseline: 1.0071x; 1.0048x over previous
; #define G5_LOAD(k0)                                                                 \
;   {                                                                                 \
;     _Pragma("unroll") for (int i_ = 0; i_ < 4; ++i_) ra[i_] = ldg16(Ap + (size_t)(i_ * 64) * lda + (k0)); \
;     _Pragma("unroll") for (int i_ = 0; i_ < 4; ++i_) rb[i_] = ldg16(Bp + (size_t)(i_ * 64) * ldb + (k0)); \
;   }
; #define G5_STORE(s)                                                                 \
;   {                                                                                 \
;     _Pragma("unroll") for (int i_ = 0; i_ < 4; ++i_) *(u32x4*)(Sw + (s) * STG + i_ * 64 * GS) = ra[i_]; \
;     _Pragma("unroll") for (int i_ = 0; i_ < 4; ++i_) *(u32x4*)(Sw + (s) * STG + 256 * GS + i_ * 64 * GS) = rb[i_]; \
;   }
; template <typename Epi>
; DI void gemm_tile512(const u16* __restrict__ A, int lda, const u16* __restrict__ Bt, int ldb, int K, char* lds_all, Epi epi) {
;     ...
;   const int nk = K >> 6;
;   __syncthreads();
;   G5_LOAD(0);
;   G5_STORE(0);
;   G5_LOAD(64);
;   __syncthreads();
;   for (int kt = 0; kt + 2 < nk; ++kt) {
;     const int cur = kt & 1;
;     G5_COMPUTE(cur);
;     G5_STORE(cur ^ 1);
;     G5_LOAD((kt + 2) << 6);
;     __syncthreads();
;   }
; DI void gemm_phase(const Params& p, int layer, int mode, int nrows, char* lds_all) {
;     ...
;   const int jb = swz ? (blockIdx.x >> 3) : blockIdx.x, nj = swz ? (gridDim.x >> 3) : gridDim.x;
;   const int per = 2 * ntn, nsr = ntm >> 1;
;   for (int i = jb;; i += nj) {
;     const int srl = i / per, rem = i - srl * per;
;     const int sr = xcd + nx * srl;
;     if (sr >= nsr) break;
;     const int tn = rem >> 1, tm = sr * 2 + (rem & 1);
;     const int m0 = tm * 256, n0 = tn * 256;
;     gemm_tile512(A + (size_t)m0 * lda, lda, Bt + (size_t)n0 * ldb, ldb, K, lds_all, [&](int half) {
.LBB0_852:
	s_sub_i32 s15, s36, s19
	s_add_i32 s15, s15, 7
	s_lshr_b32 s15, s15, 3
	s_sub_i32 s15, s15, 1
	s_sub_i32 s15, s15, s10
	s_lshl_b32 s15, s15, 3
	s_add_i32 s11, s15, s19
	s_lshl_b32 s15, s11, 9
	s_lshl_b32 s11, s23, 8
	s_and_b32 s11, s11, 0x100
	s_lshl_b32 s26, s10, 10
	s_lshl_b32 s10, s23, 7
	s_or_b32 s24, s11, s15
	s_sub_i32 s10, s10, s26
	s_and_b32 s25, s10, 0xffffff00
	s_mul_i32 s10, s24, 0x2100
	s_mul_hi_i32 s11, s24, 0x2100
	s_add_u32 s10, s50, s10
	s_addc_u32 s11, s51, s11
	s_mul_i32 s12, s25, 0x2100
	s_mul_hi_i32 s13, s25, 0x2100
	s_add_u32 s12, s30, s12
	s_addc_u32 s13, s31, s13
	s_mov_b64 s[98:99], s[10:11]
	s_mov_b64 s[100:101], s[12:13]
	v_lshrrev_b32_e32 v239, 3, v165
	v_and_b32_e32 v0, 7, v165
	v_mul_u32_u24_e32 v206, 0x2100, v239
	v_lshl_add_u32 v206, v0, 4, v206
	v_add_u32_e32 v207, 0x84000, v206
	v_add_u32_e32 v208, 0x108000, v206
	v_add_u32_e32 v238, 0x18c000, v206
	v_mul_u32_u24_e32 v180, 0x90, v239
	v_lshl_add_u32 v180, v0, 4, v180
	global_load_dwordx4 v[2:5], v206, s[98:99]
	global_load_dwordx4 v[6:9], v207, s[98:99]
	global_load_dwordx4 v[10:13], v208, s[98:99]
	global_load_dwordx4 v[14:17], v238, s[98:99]
	global_load_dwordx4 v[18:21], v206, s[100:101]
	global_load_dwordx4 v[22:25], v207, s[100:101]
	global_load_dwordx4 v[26:29], v208, s[100:101]
	global_load_dwordx4 v[30:33], v238, s[100:101]
	global_load_dwordx4 v[130:133], v206, s[98:99] offset:128
	global_load_dwordx4 v[134:137], v207, s[98:99] offset:128
	global_load_dwordx4 v[138:141], v208, s[98:99] offset:128
	global_load_dwordx4 v[142:145], v238, s[98:99] offset:128
	global_load_dwordx4 v[146:149], v206, s[100:101] offset:128
	global_load_dwordx4 v[150:153], v207, s[100:101] offset:128
	global_load_dwordx4 v[154:157], v208, s[100:101] offset:128
	global_load_dwordx4 v[158:161], v238, s[100:101] offset:128
	global_load_dwordx4 v[182:185], v206, s[98:99] offset:256
	global_load_dwordx4 v[186:189], v207, s[98:99] offset:256
	global_load_dwordx4 v[210:213], v208, s[98:99] offset:256
	global_load_dwordx4 v[240:243], v238, s[98:99] offset:256
	s_add_u32 s98, s98, 0x180
	s_addc_u32 s99, s99, 0
	s_add_u32 s100, s100, 0x100
	s_addc_u32 s101, s101, 0
	v_and_b32_e32 v239, 31, v165
	v_bfe_u32 v0, v165, 5, 1
	v_lshrrev_b32_e32 v179, 8, v165
	v_lshl_or_b32 v178, v179, 7, v239
	v_mul_u32_u24_e32 v178, 0x90, v178
	v_lshl_add_u32 v178, v0, 4, v178
	v_bfe_u32 v179, v165, 6, 2
	v_lshl_or_b32 v179, v179, 6, v239
	v_mul_u32_u24_e32 v179, 0x90, v179
	v_lshl_add_u32 v179, v0, 4, v179
	s_mov_b32 s14, 0x12000
	s_mov_b32 s15, 29
	s_barrier
	s_waitcnt vmcnt(19)
	ds_write_b128 v180, v[2:5]
	s_waitcnt vmcnt(18)
	ds_write_b128 v180, v[6:9] offset:9216
	s_waitcnt vmcnt(17)
	ds_write_b128 v180, v[10:13] offset:18432
	s_waitcnt vmcnt(16)
	ds_write_b128 v180, v[14:17] offset:27648
	s_waitcnt vmcnt(15)
	ds_write_b128 v180, v[18:21] offset:36864
	s_waitcnt vmcnt(14)
	ds_write_b128 v180, v[22:25] offset:46080
	s_waitcnt vmcnt(13)
	ds_write_b128 v180, v[26:29] offset:55296
	s_waitcnt vmcnt(12)
	ds_write_b128 v180, v[30:33] offset:64512
	v_add_u32_e32 v180, 0x12000, v180
	s_waitcnt lgkmcnt(0)
	s_barrier
	ds_read_b128 v[194:197], v179 offset:36864
	ds_read_b128 v[166:169], v178
	ds_read_b128 v[198:201], v179 offset:41472
	ds_read_b128 v[170:173], v178 offset:4608
	ds_read_b128 v[174:177], v178 offset:9216
	ds_read_b128 v[190:193], v178 offset:13824
	s_waitcnt lgkmcnt(4)
	v_mfma_f32_32x32x16_bf16 v[114:129], v[166:169], v[194:197], 0
	ds_read_b128 v[234:237], v179 offset:36896
	s_waitcnt lgkmcnt(4)
	v_mfma_f32_32x32x16_bf16 v[98:113], v[166:169], v[198:201], 0
	ds_read_b128 v[218:221], v178 offset:32
	s_waitcnt vmcnt(11)
	ds_write_b128 v180, v[130:133]
	global_load_dwordx4 v[130:133], v206, s[98:99]
	s_waitcnt lgkmcnt(5)
	v_mfma_f32_32x32x16_bf16 v[82:97], v[170:173], v[194:197], 0
	ds_read_b128 v[202:205], v179 offset:41504
	v_mfma_f32_32x32x16_bf16 v[66:81], v[170:173], v[198:201], 0
	ds_read_b128 v[222:225], v178 offset:4640
	s_waitcnt vmcnt(11)
	ds_write_b128 v180, v[134:137] offset:9216
	global_load_dwordx4 v[134:137], v207, s[98:99]
	s_waitcnt lgkmcnt(7)
	v_mfma_f32_32x32x16_bf16 v[50:65], v[174:177], v[194:197], 0
	ds_read_b128 v[226:229], v178 offset:9248
	v_mfma_f32_32x32x16_bf16 v[34:49], v[174:177], v[198:201], 0
	ds_read_b128 v[230:233], v178 offset:13856
	s_waitcnt vmcnt(11)
	ds_write_b128 v180, v[138:141] offset:18432
	global_load_dwordx4 v[138:141], v208, s[98:99]
	s_waitcnt lgkmcnt(9)
	v_mfma_f32_32x32x16_bf16 v[18:33], v[190:193], v[194:197], 0
	v_mfma_f32_32x32x16_bf16 v[2:17], v[190:193], v[198:201], 0
	s_waitcnt vmcnt(11)
	ds_write_b128 v180, v[142:145] offset:27648
	global_load_dwordx4 v[142:145], v238, s[98:99]
	s_waitcnt lgkmcnt(8)
	v_mfma_f32_32x32x16_bf16 v[114:129], v[218:221], v[234:237], v[114:129]
	ds_read_b128 v[194:197], v179 offset:36928
	s_waitcnt lgkmcnt(7)
	v_mfma_f32_32x32x16_bf16 v[98:113], v[218:221], v[202:205], v[98:113]
	ds_read_b128 v[166:169], v178 offset:64
	s_waitcnt vmcnt(11)
	ds_write_b128 v180, v[146:149] offset:36864
	global_load_dwordx4 v[146:149], v206, s[100:101]
	s_waitcnt lgkmcnt(8)
	v_mfma_f32_32x32x16_bf16 v[82:97], v[222:225], v[234:237], v[82:97]
	ds_read_b128 v[198:201], v179 offset:41536
	v_mfma_f32_32x32x16_bf16 v[66:81], v[222:225], v[202:205], v[66:81]
	ds_read_b128 v[170:173], v178 offset:4672
	s_waitcnt vmcnt(11)
	ds_write_b128 v180, v[150:153] offset:46080
	global_load_dwordx4 v[150:153], v207, s[100:101]
	s_waitcnt lgkmcnt(9)
	v_mfma_f32_32x32x16_bf16 v[50:65], v[226:229], v[234:237], v[50:65]
	ds_read_b128 v[174:177], v178 offset:9280
	v_mfma_f32_32x32x16_bf16 v[34:49], v[226:229], v[202:205], v[34:49]
	ds_read_b128 v[190:193], v178 offset:13888
	s_waitcnt vmcnt(11)
; #define G5_LOAD(k0)                                                                 \
;   {                                                                                 \
;     _Pragma("unroll") for (int i_ = 0; i_ < 4; ++i_) ra[i_] = ldg16(Ap + (size_t)(i_ * 64) * lda + (k0)); \
;     _Pragma("unroll") for (int i_ = 0; i_ < 4; ++i_) rb[i_] = ldg16(Bp + (size_t)(i_ * 64) * ldb + (k0)); \
;   }
; #define G5_STORE(s)                                                                 \
;   {                                                                                 \
;     _Pragma("unroll") for (int i_ = 0; i_ < 4; ++i_) *(u32x4*)(Sw + (s) * STG + i_ * 64 * GS) = ra[i_]; \
;     _Pragma("unroll") for (int i_ = 0; i_ < 4; ++i_) *(u32x4*)(Sw + (s) * STG + 256 * GS + i_ * 64 * GS) = rb[i_]; \
;   }
; template <typename Epi>
; DI void gemm_tile512(const u16* __restrict__ A, int lda, const u16* __restrict__ Bt, int ldb, int K, char* lds_all, Epi epi) {
;     ...
;   for (int kt = 0; kt + 2 < nk; ++kt) {
;     const int cur = kt & 1;
;     G5_COMPUTE(cur);
;     G5_STORE(cur ^ 1);
;     G5_LOAD((kt + 2) << 6);
;     __syncthreads();
;   }
	ds_write_b128 v180, v[154:157] offset:55296
	global_load_dwordx4 v[154:157], v208, s[100:101]
	s_waitcnt lgkmcnt(11)
	v_mfma_f32_32x32x16_bf16 v[18:33], v[230:233], v[234:237], v[18:33]
	v_mfma_f32_32x32x16_bf16 v[2:17], v[230:233], v[202:205], v[2:17]
	s_waitcnt vmcnt(11)
	ds_write_b128 v180, v[158:161] offset:64512
	global_load_dwordx4 v[158:161], v238, s[100:101]
	v_subrev_u32_e32 v180, s14, v180
	s_waitcnt lgkmcnt(8)
	v_mfma_f32_32x32x16_bf16 v[114:129], v[166:169], v[194:197], v[114:129]
	ds_read_b128 v[234:237], v179 offset:36960
	s_waitcnt lgkmcnt(7)
	v_mfma_f32_32x32x16_bf16 v[98:113], v[166:169], v[198:201], v[98:113]
	ds_read_b128 v[218:221], v178 offset:96
	s_waitcnt lgkmcnt(7)
	v_mfma_f32_32x32x16_bf16 v[82:97], v[170:173], v[194:197], v[82:97]
	ds_read_b128 v[202:205], v179 offset:41568
	v_mfma_f32_32x32x16_bf16 v[66:81], v[170:173], v[198:201], v[66:81]
	ds_read_b128 v[222:225], v178 offset:4704
	s_waitcnt lgkmcnt(7)
	v_mfma_f32_32x32x16_bf16 v[50:65], v[174:177], v[194:197], v[50:65]
	ds_read_b128 v[226:229], v178 offset:9312
	v_mfma_f32_32x32x16_bf16 v[34:49], v[174:177], v[198:201], v[34:49]
	ds_read_b128 v[230:233], v178 offset:13920
	v_add_u32_e32 v178, s14, v178
	v_add_u32_e32 v179, s14, v179
	s_waitcnt lgkmcnt(8)
	v_mfma_f32_32x32x16_bf16 v[18:33], v[190:193], v[194:197], v[18:33]
	v_mfma_f32_32x32x16_bf16 v[2:17], v[190:193], v[198:201], v[2:17]
	s_sub_u32 s14, 0, s14
	s_add_u32 s98, s98, 0x80
	s_addc_u32 s99, s99, 0
	s_add_u32 s100, s100, 0x80
	s_addc_u32 s101, s101, 0
	s_waitcnt lgkmcnt(0)
	s_barrier
	ds_read_b128 v[194:197], v179 offset:36864
	ds_read_b128 v[166:169], v178
	v_mfma_f32_32x32x16_bf16 v[114:129], v[218:221], v[234:237], v[114:129]
	ds_read_b128 v[198:201], v179 offset:41472
	v_mfma_f32_32x32x16_bf16 v[98:113], v[218:221], v[202:205], v[98:113]
	ds_read_b128 v[170:173], v178 offset:4608
	v_mfma_f32_32x32x16_bf16 v[82:97], v[222:225], v[234:237], v[82:97]
	ds_read_b128 v[174:177], v178 offset:9216
	v_mfma_f32_32x32x16_bf16 v[66:81], v[222:225], v[202:205], v[66:81]
	ds_read_b128 v[190:193], v178 offset:13824
	v_mfma_f32_32x32x16_bf16 v[50:65], v[226:229], v[234:237], v[50:65]
	v_mfma_f32_32x32x16_bf16 v[34:49], v[226:229], v[202:205], v[34:49]
	v_mfma_f32_32x32x16_bf16 v[18:33], v[230:233], v[234:237], v[18:33]
	v_mfma_f32_32x32x16_bf16 v[2:17], v[230:233], v[202:205], v[2:17]
	s_waitcnt lgkmcnt(4)
	v_mfma_f32_32x32x16_bf16 v[114:129], v[166:169], v[194:197], v[114:129]
	ds_read_b128 v[234:237], v179 offset:36896
	s_waitcnt lgkmcnt(4)
	v_mfma_f32_32x32x16_bf16 v[98:113], v[166:169], v[198:201], v[98:113]
	ds_read_b128 v[218:221], v178 offset:32
	s_waitcnt vmcnt(11)
	ds_write_b128 v180, v[182:185]
	global_load_dwordx4 v[182:185], v206, s[98:99]
	s_waitcnt lgkmcnt(5)
	v_mfma_f32_32x32x16_bf16 v[82:97], v[170:173], v[194:197], v[82:97]
	ds_read_b128 v[202:205], v179 offset:41504
	v_mfma_f32_32x32x16_bf16 v[66:81], v[170:173], v[198:201], v[66:81]
	ds_read_b128 v[222:225], v178 offset:4640
	s_waitcnt vmcnt(11)
	ds_write_b128 v180, v[186:189] offset:9216
	global_load_dwordx4 v[186:189], v207, s[98:99]
	s_waitcnt lgkmcnt(7)
	v_mfma_f32_32x32x16_bf16 v[50:65], v[174:177], v[194:197], v[50:65]
	ds_read_b128 v[226:229], v178 offset:9248
	v_mfma_f32_32x32x16_bf16 v[34:49], v[174:177], v[198:201], v[34:49]
	ds_read_b128 v[230:233], v178 offset:13856
	s_waitcnt vmcnt(11)
	ds_write_b128 v180, v[210:213] offset:18432
	global_load_dwordx4 v[210:213], v208, s[98:99]
	s_waitcnt lgkmcnt(9)
	v_mfma_f32_32x32x16_bf16 v[18:33], v[190:193], v[194:197], v[18:33]
	v_mfma_f32_32x32x16_bf16 v[2:17], v[190:193], v[198:201], v[2:17]
	s_waitcnt vmcnt(11)
	ds_write_b128 v180, v[240:243] offset:27648
	global_load_dwordx4 v[240:243], v238, s[98:99]
	s_waitcnt lgkmcnt(8)
	v_mfma_f32_32x32x16_bf16 v[114:129], v[218:221], v[234:237], v[114:129]
	ds_read_b128 v[194:197], v179 offset:36928
	s_waitcnt lgkmcnt(7)
	v_mfma_f32_32x32x16_bf16 v[98:113], v[218:221], v[202:205], v[98:113]
	ds_read_b128 v[166:169], v178 offset:64
	s_waitcnt vmcnt(7)
	ds_write_b128 v180, v[146:149] offset:36864
	global_load_dwordx4 v[146:149], v206, s[100:101]
	s_waitcnt lgkmcnt(8)
	v_mfma_f32_32x32x16_bf16 v[82:97], v[222:225], v[234:237], v[82:97]
	ds_read_b128 v[198:201], v179 offset:41536
	v_mfma_f32_32x32x16_bf16 v[66:81], v[222:225], v[202:205], v[66:81]
	ds_read_b128 v[170:173], v178 offset:4672
	s_waitcnt vmcnt(7)
	ds_write_b128 v180, v[150:153] offset:46080
	global_load_dwordx4 v[150:153], v207, s[100:101]
	s_waitcnt lgkmcnt(9)
	v_mfma_f32_32x32x16_bf16 v[50:65], v[226:229], v[234:237], v[50:65]
	ds_read_b128 v[174:177], v178 offset:9280
	v_mfma_f32_32x32x16_bf16 v[34:49], v[226:229], v[202:205], v[34:49]
	ds_read_b128 v[190:193], v178 offset:13888
	s_waitcnt vmcnt(7)
	ds_write_b128 v180, v[154:157] offset:55296
	global_load_dwordx4 v[154:157], v208, s[100:101]
	s_waitcnt lgkmcnt(11)
	v_mfma_f32_32x32x16_bf16 v[18:33], v[230:233], v[234:237], v[18:33]
	v_mfma_f32_32x32x16_bf16 v[2:17], v[230:233], v[202:205], v[2:17]
	s_waitcnt vmcnt(7)
	ds_write_b128 v180, v[158:161] offset:64512
	global_load_dwordx4 v[158:161], v238, s[100:101]
	v_subrev_u32_e32 v180, s14, v180
	s_waitcnt lgkmcnt(8)
	v_mfma_f32_32x32x16_bf16 v[114:129], v[166:169], v[194:197], v[114:129]
	ds_read_b128 v[234:237], v179 offset:36960
	s_waitcnt lgkmcnt(7)
	v_mfma_f32_32x32x16_bf16 v[98:113], v[166:169], v[198:201], v[98:113]
	ds_read_b128 v[218:221], v178 offset:96
	s_waitcnt lgkmcnt(7)
	v_mfma_f32_32x32x16_bf16 v[82:97], v[170:173], v[194:197], v[82:97]
	ds_read_b128 v[202:205], v179 offset:41568
	v_mfma_f32_32x32x16_bf16 v[66:81], v[170:173], v[198:201], v[66:81]
	ds_read_b128 v[222:225], v178 offset:4704
	s_waitcnt lgkmcnt(7)
	v_mfma_f32_32x32x16_bf16 v[50:65], v[174:177], v[194:197], v[50:65]
	ds_read_b128 v[226:229], v178 offset:9312
	v_mfma_f32_32x32x16_bf16 v[34:49], v[174:177], v[198:201], v[34:49]
	ds_read_b128 v[230:233], v178 offset:13920
	v_add_u32_e32 v178, s14, v178
	v_add_u32_e32 v179, s14, v179
	s_waitcnt lgkmcnt(8)
	v_mfma_f32_32x32x16_bf16 v[18:33], v[190:193], v[194:197], v[18:33]
	v_mfma_f32_32x32x16_bf16 v[2:17], v[190:193], v[198:201], v[2:17]
	s_sub_u32 s14, 0, s14
	s_add_u32 s98, s98, 0x80
	s_addc_u32 s99, s99, 0
	s_add_u32 s100, s100, 0x80
	s_addc_u32 s101, s101, 0
	s_waitcnt lgkmcnt(0)
